# adds: barrier arrival atomic-first with counted wait; idle FFN-in tail WGs convert all remaining w_in(l1) tiles (480 tiles moved out of phase 0)
# speedup vs baseline: 1.0009x; 1.0009x over previous
; __device__ __forceinline__ ConvDesc conv_desc(const Params& p, int item) {
;     const int l = item / CV_PER_LAYER; int r = item % CV_PER_LAYER;
;     unsigned char* wl = p.ws + (size_t)l * SZ_WL;
;     ConvDesc d; d.nvalid = 128;
;     if (r < 1760) { const int kt = r / 110, nt = r % 110; int nv = NIN - nt * 128; d.nvalid = nv < 0 ? 0 : (nv > 128 ? 128 : nv); d.Nsrc = NIN; d.K = D;
;         d.src = p.in[6] + (size_t)l * D * NIN + (size_t)(kt * 128) * NIN + nt * 128; d.dst = (bf16_t*)(wl + O_WIN) + (size_t)(nt * 128) * D + kt * 128; return d; }
;     r -= 1760;
;     if (r < 96) { const int kt = r >> 4, nt = r & 15; d.Nsrc = D; d.K = D;
;         d.src = p.in[14] + (size_t)l * 768 * D + (size_t)(kt * 128) * D + nt * 128; d.dst = (bf16_t*)(wl + O_WBR) + (size_t)(nt * 128) * D + kt * 128; return d; }
;     r -= 96;
;     if (r < 32) { const int kt = r >> 4, nt = r & 15; d.Nsrc = D; d.K = D;
;         d.src = p.in[15] + (size_t)l * 256 * D + (size_t)(kt * 128) * D + nt * 128; d.dst = (bf16_t*)(wl + O_WBR) + (size_t)(nt * 128) * D + 768 + kt * 128; return d; }
;     r -= 32;
;     if (r < 128) { const int kt = r >> 4, nt = r & 15; d.Nsrc = D; d.K = D;
;         d.src = p.in[16] + (size_t)l * 1024 * D + (size_t)(kt * 128) * D + nt * 128; d.dst = (bf16_t*)(wl + O_WBR) + (size_t)(nt * 128) * D + 1024 + kt * 128; return d; }
;     r -= 128;
; __device__ __forceinline__ void conv_phase(const Params& p, unsigned char* lds, int lo1, int n1, int lo2, int n2, int worker, int nworkers, bool rev2 = false) {
;     ...
;     for (;;) {
; #pragma unroll
;         for (int i = 0; i < 8; ++i) {
;             const int idx = tid + 512 * i; float* sp = st + (idx >> 5) * 129 + (idx & 31) * 4;
;             sp[0] = x4[i][0]; sp[1] = x4[i][1]; sp[2] = x4[i][2]; sp[3] = x4[i][3];
;         }
;         __syncthreads();
;         const ConvDesc dc = d;
;         const int nx = v + nworkers; const bool more = nx < ntot;
;         if (more) { d = conv_desc(p, nx < n1 ? lo1 + nx : (rev2 ? lo2 + (n2 - 1 - (nx - n1)) : lo2 + nx - n1)); conv_load(d, tid, x4); }
;         unsigned* dp = (unsigned*)(dc.dst + (size_t)(16 * w) * dc.K) + lane;
;         const float* rp = st + (2 * lane) * 129 + 16 * w;
; #pragma unroll
;         for (int q = 0; q < 16; ++q) dp[(size_t)q * (dc.K >> 1)] = pk2(rp[q], rp[129 + q]);
;         __syncthreads();
;         if (!more) break;
;         v = nx;
.LBB0_517:
	v_mad_u64_u32 v[64:65], s[10:11], s7, v48, 0
	v_mov_b32_e32 v66, v65
	v_mad_u64_u32 v[66:67], s[10:11], s7, v35, v[66:67]
	v_mov_b32_e32 v65, v66
	v_lshl_add_u64 v[64:65], v[64:65], 1, s[2:3]
	v_lshl_add_u64 v[68:69], v[64:65], 0, v[0:1]
	ds_read2_b64 v[64:67], v55 offset1:1
	ds_read2_b32 v[70:71], v55 offset0:129 offset1:130
	s_lshr_b32 s28, s7, 1
	s_lshl_b64 s[2:3], s[28:29], 2
	s_addk_i32 s4, 0x80
	s_cmpk_gt_i32 s5, 0x55f
	s_waitcnt lgkmcnt(0)
	v_cvt_pk_bf16_f32 v37, v64, v70
	flat_store_dword v[68:69], v37
	v_cvt_pk_bf16_f32 v37, v65, v71
	v_lshl_add_u64 v[64:65], v[68:69], 0, s[2:3]
	ds_read2_b32 v[68:69], v55 offset0:131 offset1:132
	flat_store_dword v[64:65], v37
	v_lshl_add_u64 v[64:65], v[64:65], 0, s[2:3]
	s_mov_b32 s7, s6
	s_mov_b32 s28, 0xbfb8aa3b
	s_waitcnt lgkmcnt(0)
	v_cvt_pk_bf16_f32 v37, v66, v68
	flat_store_dword v[64:65], v37
	v_cvt_pk_bf16_f32 v37, v67, v69
	v_lshl_add_u64 v[68:69], v[64:65], 0, s[2:3]
	flat_store_dword v[68:69], v37
	ds_read2_b64 v[64:67], v55 offset0:2 offset1:3
	ds_read2_b32 v[70:71], v55 offset0:133 offset1:134
	v_lshl_add_u64 v[68:69], v[68:69], 0, s[2:3]
	s_waitcnt lgkmcnt(0)
	v_cvt_pk_bf16_f32 v37, v64, v70
	flat_store_dword v[68:69], v37
	v_cvt_pk_bf16_f32 v37, v65, v71
	v_lshl_add_u64 v[64:65], v[68:69], 0, s[2:3]
	ds_read2_b32 v[68:69], v55 offset0:135 offset1:136
	flat_store_dword v[64:65], v37
	v_lshl_add_u64 v[64:65], v[64:65], 0, s[2:3]
	s_waitcnt lgkmcnt(0)
	v_cvt_pk_bf16_f32 v37, v66, v68
	flat_store_dword v[64:65], v37
	v_cvt_pk_bf16_f32 v37, v67, v69
	v_lshl_add_u64 v[68:69], v[64:65], 0, s[2:3]
	flat_store_dword v[68:69], v37
	ds_read2_b64 v[64:67], v55 offset0:4 offset1:5
	ds_read2_b32 v[70:71], v55 offset0:137 offset1:138
	v_lshl_add_u64 v[68:69], v[68:69], 0, s[2:3]
	s_waitcnt lgkmcnt(0)
	v_cvt_pk_bf16_f32 v37, v64, v70
	flat_store_dword v[68:69], v37
	v_cvt_pk_bf16_f32 v37, v65, v71
	v_lshl_add_u64 v[64:65], v[68:69], 0, s[2:3]
	ds_read2_b32 v[68:69], v55 offset0:139 offset1:140
	flat_store_dword v[64:65], v37
	v_lshl_add_u64 v[64:65], v[64:65], 0, s[2:3]
	s_waitcnt lgkmcnt(0)
	v_cvt_pk_bf16_f32 v37, v66, v68
	flat_store_dword v[64:65], v37
	v_cvt_pk_bf16_f32 v37, v67, v69
	v_lshl_add_u64 v[68:69], v[64:65], 0, s[2:3]
	flat_store_dword v[68:69], v37
	ds_read2_b64 v[64:67], v55 offset0:6 offset1:7
	ds_read2_b32 v[70:71], v55 offset0:141 offset1:142
	v_lshl_add_u64 v[68:69], v[68:69], 0, s[2:3]
	s_waitcnt lgkmcnt(0)
	v_cvt_pk_bf16_f32 v37, v64, v70
	flat_store_dword v[68:69], v37
	v_cvt_pk_bf16_f32 v37, v65, v71
	v_lshl_add_u64 v[64:65], v[68:69], 0, s[2:3]
	ds_read2_b32 v[68:69], v55 offset0:143 offset1:144
	flat_store_dword v[64:65], v37
	v_lshl_add_u64 v[64:65], v[64:65], 0, s[2:3]
	s_waitcnt lgkmcnt(0)
	v_cvt_pk_bf16_f32 v37, v66, v68
	flat_store_dword v[64:65], v37
	v_cvt_pk_bf16_f32 v37, v67, v69
	v_lshl_add_u64 v[64:65], v[64:65], 0, s[2:3]
	s_mov_b64 s[2:3], s[0:1]
	flat_store_dword v[64:65], v37
	s_waitcnt lgkmcnt(0)
	s_barrier
	s_cbranch_scc1 .LBB0_177
.LBB0_518:
	s_add_i32 s5, s4, 0xffffed60
	s_cmpk_gt_i32 s5, 0x55f
	s_waitcnt vmcnt(0)
	ds_write2_b32 v56, v6, v7 offset1:1
	ds_write2_b32 v56, v8, v9 offset0:2 offset1:3
	ds_write2_b32 v57, v2, v3 offset1:1
	ds_write2_b32 v57, v4, v5 offset0:2 offset1:3
	ds_write2_b32 v58, v14, v15 offset1:1
	ds_write2_b32 v58, v16, v17 offset0:2 offset1:3
	ds_write2_b32 v59, v10, v11 offset1:1
	ds_write2_b32 v59, v12, v13 offset0:2 offset1:3
	ds_write2_b32 v60, v22, v23 offset1:1
	ds_write2_b32 v60, v24, v25 offset0:2 offset1:3
	ds_write2_b32 v61, v18, v19 offset1:1
	ds_write2_b32 v61, v20, v21 offset0:2 offset1:3
	ds_write2_b32 v62, v30, v31 offset1:1
	ds_write2_b32 v62, v32, v33 offset0:2 offset1:3
	ds_write2_b32 v63, v26, v27 offset1:1
	ds_write2_b32 v63, v28, v29 offset0:2 offset1:3
	s_waitcnt lgkmcnt(0)
	s_barrier
	s_cbranch_scc1 .LBB0_517
	s_mul_hi_u32 s0, s4, 0x77975b9
	s_lshr_b32 s28, s0, 7
	s_mul_i32 s0, s28, 0x1120
	s_sub_i32 s11, s4, s0
	s_mul_i32 s1, s28, 0x8900000
	s_mul_hi_u32 s0, s28, 0x8900000
	s_add_u32 s8, s26, s1
	s_addc_u32 s10, s27, s0
	s_mov_b64 s[36:37], -1
	s_cmpk_gt_u32 s11, 0x6df
	s_mov_b64 s[42:43], -1
	s_cbranch_scc0 .LBB0_540
	s_cmpk_gt_u32 s11, 0x73f
	s_cbranch_scc0 .LBB0_537
	s_cmpk_gt_u32 s11, 0x75f
	s_cbranch_scc0 .LBB0_534
	s_cmpk_gt_u32 s11, 0x7df
	s_cbranch_scc0 .LBB0_531
	s_cmpk_gt_u32 s11, 0x8df
	s_cbranch_scc0 .LBB0_528
	s_cmpk_gt_u32 s11, 0xe5f
	s_mov_b64 s[40:41], -1
	s_cbranch_scc0 .LBB0_526
	v_readlane_b32 s40, v247, 1
	s_mul_i32 s1, s28, 0x2c00000
	v_readlane_b32 s46, v247, 7
	s_mul_hi_u32 s0, s28, 0x2c00000
	v_readlane_b32 s47, v247, 8
	s_add_u32 s6, s46, s1
	s_addc_u32 s16, s47, s0
	s_lshl_b32 s0, s11, 3
	s_and_b32 s0, s0, 0xff80
	s_addk_i32 s0, 0x8d00
	s_mov_b32 s1, s29
	s_lshl_b64 s[12:13], s[0:1], 13
	s_add_u32 s6, s6, s12
	s_addc_u32 s12, s16, s13
	s_lshl_b32 s13, s11, 7
	s_and_b32 s13, s13, 0x780
	s_lshl_b32 s16, s13, 2
	s_add_u32 s38, s6, s16
	s_addc_u32 s39, s12, 0
	s_mulk_i32 s13, 0x2c00
	s_add_u32 s6, s8, s13
	s_addc_u32 s12, s10, 0
	s_lshl_b64 s[0:1], s[0:1], 1
	s_add_u32 s0, s6, s0
	s_addc_u32 s1, s12, s1
	v_readlane_b32 s41, v247, 2
	s_add_u32 s0, s0, 0x7300000
	v_readlane_b32 s42, v247, 3
	v_readlane_b32 s43, v247, 4
	v_readlane_b32 s44, v247, 5
	v_readlane_b32 s45, v247, 6
	s_addc_u32 s1, s1, 0
	s_mov_b64 s[40:41], 0

; __device__ __forceinline__ int tidx() { int t = threadIdx.x; asm volatile("" : "+v"(t)); return t; }
; __device__ __forceinline__ ConvDesc conv_desc(const Params& p, int item) {
;     const int l = item / CV_PER_LAYER; int r = item % CV_PER_LAYER;
;     unsigned char* wl = p.ws + (size_t)l * SZ_WL;
;     ConvDesc d; d.nvalid = 128;
;     if (r < 1760) { const int kt = r / 110, nt = r % 110; int nv = NIN - nt * 128; d.nvalid = nv < 0 ? 0 : (nv > 128 ? 128 : nv); d.Nsrc = NIN; d.K = D;
;         d.src = p.in[6] + (size_t)l * D * NIN + (size_t)(kt * 128) * NIN + nt * 128; d.dst = (bf16_t*)(wl + O_WIN) + (size_t)(nt * 128) * D + kt * 128; return d; }
;     r -= 1760;
;     if (r < 96) { const int kt = r >> 4, nt = r & 15; d.Nsrc = D; d.K = D;
;         d.src = p.in[14] + (size_t)l * 768 * D + (size_t)(kt * 128) * D + nt * 128; d.dst = (bf16_t*)(wl + O_WBR) + (size_t)(nt * 128) * D + kt * 128; return d; }
;     r -= 96;
;     if (r < 32) { const int kt = r >> 4, nt = r & 15; d.Nsrc = D; d.K = D;
;         d.src = p.in[15] + (size_t)l * 256 * D + (size_t)(kt * 128) * D + nt * 128; d.dst = (bf16_t*)(wl + O_WBR) + (size_t)(nt * 128) * D + 768 + kt * 128; return d; }
;     r -= 32;
;     if (r < 128) { const int kt = r >> 4, nt = r & 15; d.Nsrc = D; d.K = D;
;         d.src = p.in[16] + (size_t)l * 1024 * D + (size_t)(kt * 128) * D + nt * 128; d.dst = (bf16_t*)(wl + O_WBR) + (size_t)(nt * 128) * D + 1024 + kt * 128; return d; }
;     r -= 128;
;     if (r < 256) { const int kt = r >> 4, nt = r & 15; d.Nsrc = D; d.K = D;
;         d.src = p.in[17] + (size_t)l * D * D + (size_t)(kt * 128) * D + nt * 128; d.dst = (bf16_t*)(wl + O_WOUT) + (size_t)(nt * 128) * D + kt * 128; return d; }
;     r -= 256;
;     if (r < 1408) { const int kt = r / 88, nt = r % 88; const int pn = nt >> 1, bj = nt & 1; d.Nsrc = 2 * DFF; d.K = D;
; __device__ __forceinline__ void conv_phase(const Params& p, unsigned char* lds, int lo1, int n1, int lo2, int n2, int worker, int nworkers, bool rev2 = false) {
;     const int tid = tidx(), lane = tid & 63, w = tid >> 6;
;     float* st = (float*)lds;
;     const int ntot = n1 + n2;
;     int v = worker;
;     if (v >= ntot) return;
;     ConvDesc d = conv_desc(p, v < n1 ? lo1 + v : (rev2 ? lo2 + (n2 - 1 - (v - n1)) : lo2 + v - n1));
;     f32x4 x4[8];
;     conv_load(d, tid, x4);
.LBB0_719:
	v_readlane_b32 s0, v245, 26
	v_mov_b32_e32 v0, v185
	s_cmpk_gt_i32 s0, 0x189f
	s_cbranch_scc1 .LBB0_806
	v_readlane_b32 s2, v245, 26
	s_add_i32 s0, s2, 0x1800
	s_sub_i32 s1, 0x189f, s2
	s_cmpk_lt_i32 s2, 0x780
	s_cselect_b32 s0, s0, s1
	s_mul_hi_i32 s1, s0, 0x77975b9
	s_lshr_b32 s2, s1, 31
	s_ashr_i32 s1, s1, 7
	s_add_i32 s30, s1, s2
	s_mul_i32 s1, s30, 0x1120
	s_sub_i32 s7, s0, s1
	s_ashr_i32 s31, s30, 31
	s_mul_i32 s1, s30, 0x8900000
	s_mul_hi_i32 s0, s30, 0x8900000
	s_add_u32 s5, s26, s1
	s_addc_u32 s6, s27, s0
	s_cmpk_gt_i32 s7, 0x6df
	s_mov_b64 s[36:37], -1
	s_cbranch_scc0 .LBB0_744
	s_cmpk_gt_u32 s7, 0x73f
	s_cbranch_scc0 .LBB0_741
	s_cmpk_gt_u32 s7, 0x75f
	s_cbranch_scc0 .LBB0_738
	s_cmpk_gt_u32 s7, 0x7df
	s_cbranch_scc0 .LBB0_735
	s_cmpk_gt_u32 s7, 0x8df
	s_cbranch_scc0 .LBB0_732
	s_cmpk_gt_u32 s7, 0xe5f
	s_mov_b64 s[24:25], -1
	s_cbranch_scc0 .LBB0_727
	v_readlane_b32 s36, v247, 1
	s_mul_i32 s1, s30, 0x2c00000
	v_readlane_b32 s42, v247, 7
	s_mul_hi_i32 s0, s30, 0x2c00000
	v_readlane_b32 s43, v247, 8
	s_add_u32 s2, s42, s1
	s_addc_u32 s3, s43, s0
	s_lshl_b32 s0, s7, 3
	s_and_b32 s0, s0, 0x7fffff80
	s_add_i32 s28, s0, 0xffff8d00
	s_lshl_b64 s[0:1], s[28:29], 13
	s_add_u32 s0, s2, s0
	s_addc_u32 s1, s3, s1
	s_lshl_b32 s2, s7, 7
	s_and_b32 s4, s2, 0x780
	s_lshl_b32 s2, s4, 2
	s_add_u32 s2, s0, s2
	s_addc_u32 s3, s1, 0
	s_mulk_i32 s4, 0x2c00
	s_add_u32 s4, s5, s4
	s_addc_u32 s8, s6, 0
	s_lshl_b64 s[0:1], s[28:29], 1
	s_add_u32 s0, s4, s0
	s_addc_u32 s1, s8, s1
	s_add_u32 s0, s0, 0x7300000
	v_readlane_b32 s37, v247, 2
	v_readlane_b32 s38, v247, 3
	v_readlane_b32 s39, v247, 4
	v_readlane_b32 s40, v247, 5
	v_readlane_b32 s41, v247, 6
	s_addc_u32 s1, s1, 0
	s_mov_b64 s[24:25], 0

; __device__ __forceinline__ unsigned pk2(float lo, float hi) { const f32v2_t v = {lo, hi}; return __builtin_bit_cast(unsigned, __builtin_convertvector(v, bf16v2_t)); }
; __device__ __forceinline__ void conv_phase(const Params& p, unsigned char* lds, int lo1, int n1, int lo2, int n2, int worker, int nworkers, bool rev2 = false) {
;     ...
;     for (;;) {
; #pragma unroll
;         for (int i = 0; i < 8; ++i) {
;             const int idx = tid + 512 * i; float* sp = st + (idx >> 5) * 129 + (idx & 31) * 4;
;             sp[0] = x4[i][0]; sp[1] = x4[i][1]; sp[2] = x4[i][2]; sp[3] = x4[i][3];
;         }
;         __syncthreads();
;         const ConvDesc dc = d;
;         const int nx = v + nworkers; const bool more = nx < ntot;
;         if (more) { d = conv_desc(p, nx < n1 ? lo1 + nx : (rev2 ? lo2 + (n2 - 1 - (nx - n1)) : lo2 + nx - n1)); conv_load(d, tid, x4); }
;         unsigned* dp = (unsigned*)(dc.dst + (size_t)(16 * w) * dc.K) + lane;
;         const float* rp = st + (2 * lane) * 129 + 16 * w;
; #pragma unroll
;         for (int q = 0; q < 16; ++q) dp[(size_t)q * (dc.K >> 1)] = pk2(rp[q], rp[129 + q]);
.LBB0_762:
	s_or_b64 exec, exec, s[30:31]
	v_and_b32_e32 v64, 63, v0
	v_ashrrev_i32_e32 v0, 2, v0
	v_and_b32_e32 v50, -16, v0
	v_mul_u32_u24_e32 v0, 0x408, v64
	v_lshlrev_b32_e32 v41, 2, v50
	s_movk_i32 s2, 0x204
	v_add3_u32 v55, 0, v0, v41
	v_mul_lo_u32 v0, v34, s2
	v_mul_lo_u32 v57, v38, s2
	v_mul_lo_u32 v58, v40, s2
	v_mul_lo_u32 v59, v42, s2
	v_mul_lo_u32 v60, v44, s2
	v_mul_lo_u32 v61, v46, s2
	v_mul_lo_u32 v62, v48, s2
	v_mul_lo_u32 v63, v52, s2
	v_readlane_b32 s2, v245, 26
	v_lshl_add_u32 v37, v39, 2, 0
	s_add_i32 s2, s96, s2
	v_sub_u32_e32 v54, 0x3610, v39
	v_ashrrev_i32_e32 v39, 31, v50
	v_ashrrev_i32_e32 v41, 31, v38
	v_ashrrev_i32_e32 v43, 31, v40
	v_ashrrev_i32_e32 v45, 31, v42
	v_ashrrev_i32_e32 v47, 31, v44
	v_ashrrev_i32_e32 v49, 31, v46
	v_ashrrev_i32_e32 v51, 31, v48
	s_sub_i32 s5, 0x189f, s2
	v_add_u32_e32 v56, v37, v0
	v_add_u32_e32 v57, v37, v57
	v_add_u32_e32 v58, v37, v58
	v_add_u32_e32 v59, v37, v59
	v_add_u32_e32 v60, v37, v60
	v_add_u32_e32 v61, v37, v61
	v_add_u32_e32 v62, v37, v62
	v_add_u32_e32 v63, v37, v63
	v_lshlrev_b32_e32 v0, 2, v64
	s_mov_b64 s[24:25], s[0:1]
	s_mov_b32 s6, s4
	s_branch .LBB0_765

; __device__ __forceinline__ ConvDesc conv_desc(const Params& p, int item) {
;     const int l = item / CV_PER_LAYER; int r = item % CV_PER_LAYER;
;     unsigned char* wl = p.ws + (size_t)l * SZ_WL;
;     ConvDesc d; d.nvalid = 128;
;     if (r < 1760) { const int kt = r / 110, nt = r % 110; int nv = NIN - nt * 128; d.nvalid = nv < 0 ? 0 : (nv > 128 ? 128 : nv); d.Nsrc = NIN; d.K = D;
;         d.src = p.in[6] + (size_t)l * D * NIN + (size_t)(kt * 128) * NIN + nt * 128; d.dst = (bf16_t*)(wl + O_WIN) + (size_t)(nt * 128) * D + kt * 128; return d; }
;     r -= 1760;
;     if (r < 96) { const int kt = r >> 4, nt = r & 15; d.Nsrc = D; d.K = D;
;         d.src = p.in[14] + (size_t)l * 768 * D + (size_t)(kt * 128) * D + nt * 128; d.dst = (bf16_t*)(wl + O_WBR) + (size_t)(nt * 128) * D + kt * 128; return d; }
;     r -= 96;
;     if (r < 32) { const int kt = r >> 4, nt = r & 15; d.Nsrc = D; d.K = D;
;         d.src = p.in[15] + (size_t)l * 256 * D + (size_t)(kt * 128) * D + nt * 128; d.dst = (bf16_t*)(wl + O_WBR) + (size_t)(nt * 128) * D + 768 + kt * 128; return d; }
;     r -= 32;
;     if (r < 128) { const int kt = r >> 4, nt = r & 15; d.Nsrc = D; d.K = D;
;         d.src = p.in[16] + (size_t)l * 1024 * D + (size_t)(kt * 128) * D + nt * 128; d.dst = (bf16_t*)(wl + O_WBR) + (size_t)(nt * 128) * D + 1024 + kt * 128; return d; }
;     r -= 128;
;     if (r < 256) { const int kt = r >> 4, nt = r & 15; d.Nsrc = D; d.K = D;
;         d.src = p.in[17] + (size_t)l * D * D + (size_t)(kt * 128) * D + nt * 128; d.dst = (bf16_t*)(wl + O_WOUT) + (size_t)(nt * 128) * D + kt * 128; return d; }
;     r -= 256;
; __device__ __forceinline__ void conv_phase(const Params& p, unsigned char* lds, int lo1, int n1, int lo2, int n2, int worker, int nworkers, bool rev2 = false) {
;     ...
;     for (;;) {
; #pragma unroll
;         for (int i = 0; i < 8; ++i) {
;             const int idx = tid + 512 * i; float* sp = st + (idx >> 5) * 129 + (idx & 31) * 4;
;             sp[0] = x4[i][0]; sp[1] = x4[i][1]; sp[2] = x4[i][2]; sp[3] = x4[i][3];
;         }
;         __syncthreads();
;         const ConvDesc dc = d;
;         const int nx = v + nworkers; const bool more = nx < ntot;
;         if (more) { d = conv_desc(p, nx < n1 ? lo1 + nx : (rev2 ? lo2 + (n2 - 1 - (nx - n1)) : lo2 + nx - n1)); conv_load(d, tid, x4); }
.LBB0_765:
	v_readlane_b32 s2, v245, 26
	s_add_i32 s2, s2, s96
	s_cmpk_gt_i32 s2, 0x189f
	v_writelane_b32 v245, s2, 26
	s_cselect_b64 s[2:3], -1, 0
	s_and_b64 vcc, exec, s[2:3]
	s_waitcnt vmcnt(0)
	ds_write2_b32 v56, v6, v7 offset1:1
	ds_write2_b32 v56, v8, v9 offset0:2 offset1:3
	ds_write2_b32 v57, v2, v3 offset1:1
	ds_write2_b32 v57, v4, v5 offset0:2 offset1:3
	ds_write2_b32 v58, v14, v15 offset1:1
	ds_write2_b32 v58, v16, v17 offset0:2 offset1:3
	ds_write2_b32 v59, v10, v11 offset1:1
	ds_write2_b32 v59, v12, v13 offset0:2 offset1:3
	ds_write2_b32 v60, v22, v23 offset1:1
	ds_write2_b32 v60, v24, v25 offset0:2 offset1:3
	ds_write2_b32 v61, v18, v19 offset1:1
	ds_write2_b32 v61, v20, v21 offset0:2 offset1:3
	ds_write2_b32 v62, v30, v31 offset1:1
	ds_write2_b32 v62, v32, v33 offset0:2 offset1:3
	ds_write2_b32 v63, v26, v27 offset1:1
	ds_write2_b32 v63, v28, v29 offset0:2 offset1:3
	s_waitcnt lgkmcnt(0)
	s_barrier
	s_cbranch_vccnz .LBB0_764
	v_readlane_b32 s7, v245, 26
	s_add_i32 s6, s7, 0x1800
	s_cmpk_lt_i32 s7, 0x780
	s_cselect_b32 s6, s6, s5
	s_mul_hi_i32 s7, s6, 0x77975b9
	s_lshr_b32 s8, s7, 31
	s_ashr_i32 s7, s7, 7
	s_add_i32 s40, s7, s8
	s_mul_i32 s7, s40, 0x1120
	s_sub_i32 s10, s6, s7
	s_ashr_i32 s41, s40, 31
	s_mul_i32 s7, s40, 0x8900000
	s_mul_hi_i32 s6, s40, 0x8900000
	s_add_u32 s7, s26, s7
	s_addc_u32 s8, s27, s6
	s_mov_b64 s[30:31], -1
	s_cmpk_gt_i32 s10, 0x6df
	s_mov_b64 s[42:43], -1
	s_cbranch_scc0 .LBB0_787
	s_cmpk_gt_u32 s10, 0x73f
	s_cbranch_scc0 .LBB0_784
	s_cmpk_gt_u32 s10, 0x75f
	s_cbranch_scc0 .LBB0_781
	s_cmpk_gt_u32 s10, 0x7df
	s_cbranch_scc0 .LBB0_778
	s_cmpk_gt_u32 s10, 0x8df
	s_cbranch_scc0 .LBB0_775
	s_cmpk_gt_u32 s10, 0xe5f
	s_mov_b64 s[38:39], -1
	s_cbranch_scc0 .LBB0_773
	v_readlane_b32 s44, v247, 1
	s_mul_i32 s11, s40, 0x2c00000
	v_readlane_b32 s50, v247, 7
	s_mul_hi_i32 s6, s40, 0x2c00000
	v_readlane_b32 s51, v247, 8
	s_add_u32 s11, s50, s11
	s_addc_u32 s6, s51, s6
	s_lshl_b32 s12, s10, 3
	s_and_b32 s12, s12, 0x7fffff80
	s_add_i32 s28, s12, 0xffff8d00
	s_lshl_b64 s[12:13], s[28:29], 13
	s_add_u32 s11, s11, s12
	s_addc_u32 s6, s6, s13
	s_lshl_b32 s12, s10, 7
	s_and_b32 s12, s12, 0x780
	s_lshl_b32 s13, s12, 2
	s_add_u32 s36, s11, s13
	s_addc_u32 s37, s6, 0
	s_mulk_i32 s12, 0x2c00
	s_add_u32 s6, s7, s12
	s_addc_u32 s11, s8, 0
	s_lshl_b64 s[12:13], s[28:29], 1
	s_add_u32 s6, s6, s12
	s_addc_u32 s11, s11, s13
	s_add_u32 s24, s6, 0x7300000
	v_readlane_b32 s45, v247, 2
	v_readlane_b32 s46, v247, 3
	v_readlane_b32 s47, v247, 4
	v_readlane_b32 s48, v247, 5
	v_readlane_b32 s49, v247, 6
	s_addc_u32 s25, s11, 0
	s_mov_b64 s[38:39], 0
